# hand-written SGU phase: weights resident in VGPRs, gamma/beta/bias in LDS, real 1-item-ahead prefetch, tree reductions
# speedup vs baseline: 1.0368x; 1.0368x over previous
; __device__ __forceinline__ void fill_cb(const float* C, int P0, char* cb) {
;     ...
;     for (int i = threadIdx.x * 4; i < n; i += 2048) { const f32x4 c = *(const f32x4*)(C + i); u32x4 o0, o1;
; #pragma unroll
;         for (int j = 0; j < 4; ++j) { const float x = (ref - c[j]) * INV_SCALE; const unsigned u1 = __float_as_uint(x) & 0xffff0000u; const float r1 = x - __uint_as_float(u1);
;             const unsigned u2 = __float_as_uint(r1) & 0xffff0000u; const float r2 = r1 - __uint_as_float(u2); const unsigned u3 = cvtpk(r2, 0.f) & 0xffffu;
;             const unsigned w0 = (u1 >> 16) | u2, w1 = u3;
;             if (j < 2) { o0[2 * j] = w0; o0[2 * j + 1] = w1; } else { o1[2 * (j - 2)] = w0; o1[2 * (j - 2) + 1] = w1; } }
;         *(u32x4*)(cb + (size_t)i * 8) = o0; *(u32x4*)(cb + (size_t)i * 8 + 16) = o1; }
; __device__ __forceinline__ void sgu_item(LAS unsigned char* lds, const bf16* VA, bf16* AO, const bf16* ZA, const bf16* WSM, const float* ln_g, const float* ln_b, const float* b_sp, ...
;     const int r0 = rb * 128;
;     v4u ureg[4], zreg[4];
;     {
;         const int row = tid >> 2, q = tid & 3;
;         const v4u* up0 = (const v4u*)(AO + (size_t)(r0 + row) * 2048 + g * 128 + q * 32);
;         const v4u* zp0 = (const v4u*)(ZA + (size_t)(r0 + row) * 1024 + g * 128 + q * 32);
; #pragma unroll
;         for (int i = 0; i < 4; ++i) { ureg[i] = up0[i]; zreg[i] = zp0[i]; }
;     }
;     {
;         const int row = tid >> 2, q = tid & 3;
;         float v[32];
; #pragma unroll
;         for (int i = 0; i < 4; ++i) { const v4u w = vin[i];
;             v[8 * i + 0] = __uint_as_float(w.x << 16); v[8 * i + 1] = __uint_as_float(w.x & 0xffff0000u); v[8 * i + 2] = __uint_as_float(w.y << 16); v[8 * i + 3] = __uint_as_float(w.y & 0xffff0000u);
;             v[8 * i + 4] = __uint_as_float(w.z << 16); v[8 * i + 5] = __uint_as_float(w.z & 0xffff0000u); v[8 * i + 6] = __uint_as_float(w.w << 16); v[8 * i + 7] = __uint_as_float(w.w & 0xffff0000u); }
;         float s = 0.f;
; #pragma unroll
;         for (int i = 0; i < 32; ++i) s += v[i];
;         s += __shfl_xor(s, 1); s += __shfl_xor(s, 2);
;         const float mu = s * (1.f / 128.f); float s2 = 0.f;
; #pragma unroll
;         for (int i = 0; i < 32; ++i) { v[i] -= mu; s2 += v[i] * v[i]; }
;         s2 += __shfl_xor(s2, 1); s2 += __shfl_xor(s2, 2);
;         const float rstd = 1.0f / sqrtf(s2 * (1.f / 128.f) + EPS);
.LBB0_262:
	global_load_dwordx4 v[8:11], v[2:3], off
	v_add_u32_e32 v6, 0x800, v6
	v_add_u32_e32 v7, -16, v5
	v_cmp_le_i32_e32 vcc, s14, v6
	v_lshl_add_u64 v[2:3], v[2:3], 0, s[18:19]
	s_or_b64 s[70:71], vcc, s[70:71]
	s_waitcnt vmcnt(0)
	v_sub_f32_e32 v8, v4, v8
	v_sub_f32_e32 v9, v4, v9
	v_sub_f32_e32 v10, v4, v10
	v_sub_f32_e32 v11, v4, v11
	v_mul_f32_e32 v12, 0x413504f3, v8
	v_mul_f32_e32 v13, 0x413504f3, v9
	v_mul_f32_e32 v14, 0x413504f3, v10
	v_mul_f32_e32 v15, 0x413504f3, v11
	v_and_b32_e32 v16, 0xffff0000, v12
	v_and_b32_e32 v17, 0xffff0000, v13
	v_and_b32_e32 v18, 0xffff0000, v14
	v_and_b32_e32 v19, 0xffff0000, v15
	v_fma_f32 v8, v8, s81, -v16
	v_fma_f32 v9, v9, s81, -v17
	v_fma_f32 v16, v10, s81, -v18
	v_fma_f32 v11, v11, s81, -v19
	v_and_b32_e32 v10, 0xffff0000, v8
	v_and_b32_e32 v17, 0xffff0000, v9
	v_and_b32_e32 v18, 0xffff0000, v16
	v_and_b32_e32 v19, 0xffff0000, v11
	v_sub_f32_e32 v20, v8, v10
	v_or_b32_sdwa v8, v10, v12 dst_sel:DWORD dst_unused:UNUSED_PAD src0_sel:DWORD src1_sel:WORD_1
	v_sub_f32_e32 v9, v9, v17
	v_or_b32_sdwa v10, v17, v13 dst_sel:DWORD dst_unused:UNUSED_PAD src0_sel:DWORD src1_sel:WORD_1
	v_sub_f32_e32 v13, v16, v18
	v_sub_f32_e32 v11, v11, v19
	v_or_b32_sdwa v12, v18, v14 dst_sel:DWORD dst_unused:UNUSED_PAD src0_sel:DWORD src1_sel:WORD_1
	v_or_b32_sdwa v14, v19, v15 dst_sel:DWORD dst_unused:UNUSED_PAD src0_sel:DWORD src1_sel:WORD_1
	v_cvt_pk_bf16_f32 v15, v20, v183
	v_cvt_pk_bf16_f32 v16, v9, v183
	v_cvt_pk_bf16_f32 v13, v13, v183
	v_cvt_pk_bf16_f32 v17, v11, v183
	s_nop 0
	v_and_b32_e32 v9, 0xffff, v15
	v_and_b32_e32 v11, 0xffff, v16
	v_and_b32_e32 v13, 0xffff, v13
	v_and_b32_e32 v15, 0xffff, v17
	ds_write_b128 v7, v[8:11]
	ds_write_b128 v5, v[12:15]
	v_add_u32_e32 v5, 0x4000, v5
	s_andn2_b64 exec, exec, s[70:71]
	s_cbranch_execnz .LBB0_262
	s_branch .LBB0_224
.LBB0_263:
	s_waitcnt vmcnt(0)
	s_barrier
.LBB0_271:
.Lsgu_entry:
	s_cmpk_gt_i32 s86, 0x7ff
	s_cbranch_scc1 .Lsgu_done
	v_lshrrev_b32_e32 v10, 2, v0
	v_and_b32_e32 v11, 3, v0
	v_lshlrev_b32_e32 v12, 6, v11
	v_and_b32_e32 v13, 15, v0
	v_bfe_u32 v14, v0, 4, 2
	v_lshl_or_b32 v1, v10, 11, v12
	v_lshl_or_b32 v2, v10, 12, v12
	v_mul_u32_u24_e32 v3, 0x104, v10
	v_add_u32_e32 v3, v3, v12
	v_mul_u32_u24_e32 v4, 0x820, v14
	v_lshl_add_u32 v4, v13, 1, v4
	s_lshl_b32 s22, s88, 5
	v_add_u32_e32 v4, s22, v4
	v_mul_u32_u24_e32 v5, 0x210, v13
	v_lshl_add_u32 v5, v14, 4, v5
	s_lshl_b32 s22, s88, 6
	s_add_i32 s22, s22, 33280
	v_add_u32_e32 v5, s22, v5
	v_mul_u32_u24_e32 v6, 0x210, v10
	v_lshl_add_u32 v6, v11, 7, v6
	v_add_u32_e32 v6, 33280, v6
	v_lshlrev_b32_e32 v7, 7, v11
	v_add_u32_e32 v7, 101376, v7
	v_lshlrev_b32_e32 v8, 2, v13
	v_add_u32_e32 v8, 102400, v8
	v_lshlrev_b32_e32 v9, 8, v13
	v_lshl_add_u32 v9, v14, 4, v9
	s_mov_b32 s4, s86
	s_mov_b32 s6, -1
	s_lshr_b32 s22, s4, 3
	s_and_b32 s23, s4, 7
	s_lshl_b32 s23, s23, 8
	s_lshl_b32 s62, s22, 18
	s_add_u32 s62, s62, s23
	s_add_u32 s14, s46, s62
	s_addc_u32 s15, s47, 0
	s_add_u32 s18, s50, s62
	s_addc_u32 s19, s51, 0
	s_lshl_b32 s62, s22, 19
	s_add_u32 s62, s62, s23
	s_add_u32 s16, s40, s62
	s_addc_u32 s17, s41, 0
	global_load_dwordx4 v[10:13], v1, s[14:15] offset:0
	global_load_dwordx4 v[14:17], v1, s[14:15] offset:16
	global_load_dwordx4 v[18:21], v1, s[14:15] offset:32
	global_load_dwordx4 v[22:25], v1, s[14:15] offset:48
	global_load_dwordx4 v[26:29], v2, s[16:17] offset:0
	global_load_dwordx4 v[30:33], v2, s[16:17] offset:16
	global_load_dwordx4 v[34:37], v2, s[16:17] offset:32
	global_load_dwordx4 v[38:41], v2, s[16:17] offset:48
	global_load_dwordx4 v[42:45], v1, s[18:19] offset:0
	global_load_dwordx4 v[46:49], v1, s[18:19] offset:16
	global_load_dwordx4 v[50:53], v1, s[18:19] offset:32
	global_load_dwordx4 v[54:57], v1, s[18:19] offset:48
.Lsgu_item:
	s_mov_b64 s[12:13], s[16:17]
	s_and_b32 s7, s4, 7
	s_cmp_eq_u32 s7, s6
	s_cbranch_scc1 .Lsgu_gok
	s_mov_b32 s6, s7
	s_lshl_b32 s22, s7, 15
	s_add_u32 s20, s28, 0x300000
	s_addc_u32 s21, s29, 0
	s_add_u32 s20, s20, s22
	s_addc_u32 s21, s21, 0
	global_load_dwordx4 v[160:163], v9, s[20:21] offset:0
	global_load_dwordx4 v[164:167], v9, s[20:21] offset:64
	s_add_u32 s20, s20, 0x1000
	s_addc_u32 s21, s21, 0
	global_load_dwordx4 v[168:171], v9, s[20:21] offset:0
	global_load_dwordx4 v[172:175], v9, s[20:21] offset:64
	s_add_u32 s20, s20, 0x1000
	s_addc_u32 s21, s21, 0
	global_load_dwordx4 v[176:179], v9, s[20:21] offset:0
	global_load_dwordx4 v[180:183], v9, s[20:21] offset:64
	s_add_u32 s20, s20, 0x1000
	s_addc_u32 s21, s21, 0
	global_load_dwordx4 v[184:187], v9, s[20:21] offset:0
	global_load_dwordx4 v[188:191], v9, s[20:21] offset:64
	s_add_u32 s20, s20, 0x1000
	s_addc_u32 s21, s21, 0
	global_load_dwordx4 v[192:195], v9, s[20:21] offset:0
	global_load_dwordx4 v[196:199], v9, s[20:21] offset:64
	global_load_dwordx4 v[200:203], v9, s[20:21] offset:128
	global_load_dwordx4 v[204:207], v9, s[20:21] offset:192
	s_add_u32 s20, s20, 0x1000
	s_addc_u32 s21, s21, 0
	global_load_dwordx4 v[208:211], v9, s[20:21] offset:0
	global_load_dwordx4 v[212:215], v9, s[20:21] offset:64
	global_load_dwordx4 v[216:219], v9, s[20:21] offset:128
	global_load_dwordx4 v[220:223], v9, s[20:21] offset:192
	s_add_u32 s20, s20, 0x1000
	s_addc_u32 s21, s21, 0
	global_load_dwordx4 v[224:227], v9, s[20:21] offset:0
	global_load_dwordx4 v[228:231], v9, s[20:21] offset:64
	global_load_dwordx4 v[232:235], v9, s[20:21] offset:128
	global_load_dwordx4 v[236:239], v9, s[20:21] offset:192
	s_add_u32 s20, s20, 0x1000
	s_addc_u32 s21, s21, 0
	global_load_dwordx4 v[240:243], v9, s[20:21] offset:0
	global_load_dwordx4 v[244:247], v9, s[20:21] offset:64
	global_load_dwordx4 v[248:251], v9, s[20:21] offset:128
	global_load_dwordx4 v[252:255], v9, s[20:21] offset:192
	v_cmp_gt_u32_e32 vcc, 0x80, v0
	s_nop 3
	s_and_saveexec_b64 s[22:23], vcc
	v_lshlrev_b32_e32 v158, 2, v0
	s_lshl_b32 s62, s7, 9
	v_add_u32_e32 v159, 101376, v158
	v_add_u32_e32 v158, s62, v158
	global_load_dword v154, v158, s[42:43]
	global_load_dword v155, v158, s[44:45]
	global_load_dword v156, v158, s[48:49]
	s_waitcnt vmcnt(0)
	ds_write_b32 v159, v154
	ds_write_b32 v159, v155 offset:512
	ds_write_b32 v159, v156 offset:1024
	s_or_b64 exec, exec, s[22:23]
	s_waitcnt vmcnt(0) lgkmcnt(0)
	s_barrier
; #define LAS __attribute__((address_space(3)))
; __device__ __forceinline__ unsigned pk2(float lo, float hi) { return pg8::cvt_pk_bf16_c(lo, hi); }
; __device__ __forceinline__ void sgu_item(LAS unsigned char* lds, const bf16* VA, bf16* AO, const bf16* ZA, const bf16* WSM, const float* ln_g, const float* ln_b, const float* b_sp, ...
;     ...
;     {
;         const int row = tid >> 2, q = tid & 3;
;         float v[32];
; #pragma unroll
;         for (int i = 0; i < 4; ++i) { const v4u w = vin[i];
;             v[8 * i + 0] = __uint_as_float(w.x << 16); v[8 * i + 1] = __uint_as_float(w.x & 0xffff0000u); v[8 * i + 2] = __uint_as_float(w.y << 16); v[8 * i + 3] = __uint_as_float(w.y & 0xffff0000u);
;             v[8 * i + 4] = __uint_as_float(w.z << 16); v[8 * i + 5] = __uint_as_float(w.z & 0xffff0000u); v[8 * i + 6] = __uint_as_float(w.w << 16); v[8 * i + 7] = __uint_as_float(w.w & 0xffff0000u); }
;         float s = 0.f;
; #pragma unroll
;         for (int i = 0; i < 32; ++i) s += v[i];
;         s += __shfl_xor(s, 1); s += __shfl_xor(s, 2);
;         const float mu = s * (1.f / 128.f); float s2 = 0.f;
; #pragma unroll
;         for (int i = 0; i < 32; ++i) { v[i] -= mu; s2 += v[i] * v[i]; }
;         s2 += __shfl_xor(s2, 1); s2 += __shfl_xor(s2, 2);
;         const float rstd = 1.0f / sqrtf(s2 * (1.f / 128.f) + EPS);
;         const f32x4* gp = (const f32x4*)(ln_g + g * 128 + q * 32); const f32x4* bp = (const f32x4*)(ln_b + g * 128 + q * 32);
;         LAS unsigned* dst = (LAS unsigned*)(lds + row * VN_PITCH + q * 64);
; #pragma unroll
;         for (int i = 0; i < 8; ++i) { const f32x4 gg = gp[i], bb = bp[i];
;             dst[2 * i] = pk2(v[4 * i] * rstd * gg.x + bb.x, v[4 * i + 1] * rstd * gg.y + bb.y);
;             dst[2 * i + 1] = pk2(v[4 * i + 2] * rstd * gg.z + bb.z, v[4 * i + 3] * rstd * gg.w + bb.w); }
;     }
;     __syncthreads();
;     if (has_next) {
;         const int row = tid >> 2, q = tid & 3;
;         const v4u* vp = (const v4u*)(VA + (size_t)(rbn * 128 + row) * 1024 + gn * 128 + q * 32);
; #pragma unroll
;         for (int i = 0; i < 4; ++i) vin[i] = vp[i];
;     }
.Lsgu_gok:
	s_mov_b32 s21, 0x5040100
	s_add_i32 s5, s4, s3
	s_cmpk_lt_i32 s5, 0x800
	s_cselect_b32 s20, 1, 0
	s_cbranch_scc0 .Lsgu_noaddr
	s_lshr_b32 s22, s5, 3
	s_and_b32 s23, s5, 7
	s_lshl_b32 s23, s23, 8
	s_lshl_b32 s62, s22, 18
	s_add_u32 s62, s62, s23
	s_add_u32 s14, s46, s62
	s_addc_u32 s15, s47, 0
	s_add_u32 s18, s50, s62
	s_addc_u32 s19, s51, 0
	s_lshl_b32 s62, s22, 19
	s_add_u32 s62, s62, s23
	s_add_u32 s16, s40, s62
	s_addc_u32 s17, s41, 0
.Lsgu_noaddr:
	s_waitcnt vmcnt(12)
	v_lshlrev_b32_e32 v58, 16, v10
	v_and_b32_e32 v59, 0xffff0000, v10
	v_lshlrev_b32_e32 v60, 16, v11
	v_and_b32_e32 v61, 0xffff0000, v11
	v_lshlrev_b32_e32 v62, 16, v12
	v_and_b32_e32 v63, 0xffff0000, v12
	v_lshlrev_b32_e32 v64, 16, v13
	v_and_b32_e32 v65, 0xffff0000, v13
	v_lshlrev_b32_e32 v66, 16, v14
	v_and_b32_e32 v67, 0xffff0000, v14
	v_lshlrev_b32_e32 v68, 16, v15
	v_and_b32_e32 v69, 0xffff0000, v15
	v_lshlrev_b32_e32 v70, 16, v16
	v_and_b32_e32 v71, 0xffff0000, v16
	v_lshlrev_b32_e32 v72, 16, v17
	v_and_b32_e32 v73, 0xffff0000, v17
	v_lshlrev_b32_e32 v74, 16, v18
	v_and_b32_e32 v75, 0xffff0000, v18
	v_lshlrev_b32_e32 v76, 16, v19
	v_and_b32_e32 v77, 0xffff0000, v19
	v_lshlrev_b32_e32 v78, 16, v20
	v_and_b32_e32 v79, 0xffff0000, v20
	v_lshlrev_b32_e32 v80, 16, v21
	v_and_b32_e32 v81, 0xffff0000, v21
	v_lshlrev_b32_e32 v82, 16, v22
	v_and_b32_e32 v83, 0xffff0000, v22
	v_lshlrev_b32_e32 v84, 16, v23
	v_and_b32_e32 v85, 0xffff0000, v23
	v_lshlrev_b32_e32 v86, 16, v24
	v_and_b32_e32 v87, 0xffff0000, v24
	v_lshlrev_b32_e32 v88, 16, v25
	v_and_b32_e32 v89, 0xffff0000, v25
	s_cmp_lg_u32 s20, 0
	s_cbranch_scc0 .Lsgu_novin
	global_load_dwordx4 v[10:13], v1, s[14:15] offset:0
	global_load_dwordx4 v[14:17], v1, s[14:15] offset:16
	global_load_dwordx4 v[18:21], v1, s[14:15] offset:32
	global_load_dwordx4 v[22:25], v1, s[14:15] offset:48
.Lsgu_novin:
	v_pk_add_f32 v[90:91], v[58:59], v[60:61]
	v_pk_add_f32 v[92:93], v[62:63], v[64:65]
	v_pk_add_f32 v[94:95], v[66:67], v[68:69]
	v_pk_add_f32 v[96:97], v[70:71], v[72:73]
	v_pk_add_f32 v[98:99], v[74:75], v[76:77]
	v_pk_add_f32 v[100:101], v[78:79], v[80:81]
	v_pk_add_f32 v[102:103], v[82:83], v[84:85]
	v_pk_add_f32 v[104:105], v[86:87], v[88:89]
	v_pk_add_f32 v[90:91], v[90:91], v[98:99]
	v_pk_add_f32 v[92:93], v[92:93], v[100:101]
	v_pk_add_f32 v[94:95], v[94:95], v[102:103]
	v_pk_add_f32 v[96:97], v[96:97], v[104:105]
	v_pk_add_f32 v[90:91], v[90:91], v[94:95]
	v_pk_add_f32 v[92:93], v[92:93], v[96:97]
	v_pk_add_f32 v[90:91], v[90:91], v[92:93]
	s_nop 0
	v_add_f32_e32 v158, v90, v91
	s_nop 1
	v_add_f32_dpp v159, v158, v158 quad_perm:[1,0,3,2] row_mask:0xf bank_mask:0xf
	s_nop 1
	v_add_f32_dpp v158, v159, v159 quad_perm:[2,3,0,1] row_mask:0xf bank_mask:0xf
	s_nop 0
	v_mul_f32_e32 v154, 0x3c000000, v158
	s_nop 0
	v_pk_add_f32 v[58:59], v[58:59], v[154:155] op_sel_hi:[1,0] neg_lo:[0,1] neg_hi:[0,1]
	v_pk_add_f32 v[60:61], v[60:61], v[154:155] op_sel_hi:[1,0] neg_lo:[0,1] neg_hi:[0,1]
	v_pk_add_f32 v[62:63], v[62:63], v[154:155] op_sel_hi:[1,0] neg_lo:[0,1] neg_hi:[0,1]
	v_pk_add_f32 v[64:65], v[64:65], v[154:155] op_sel_hi:[1,0] neg_lo:[0,1] neg_hi:[0,1]
	v_pk_add_f32 v[66:67], v[66:67], v[154:155] op_sel_hi:[1,0] neg_lo:[0,1] neg_hi:[0,1]
	v_pk_add_f32 v[68:69], v[68:69], v[154:155] op_sel_hi:[1,0] neg_lo:[0,1] neg_hi:[0,1]
	v_pk_add_f32 v[70:71], v[70:71], v[154:155] op_sel_hi:[1,0] neg_lo:[0,1] neg_hi:[0,1]
	v_pk_add_f32 v[72:73], v[72:73], v[154:155] op_sel_hi:[1,0] neg_lo:[0,1] neg_hi:[0,1]
	v_pk_add_f32 v[74:75], v[74:75], v[154:155] op_sel_hi:[1,0] neg_lo:[0,1] neg_hi:[0,1]
	v_pk_add_f32 v[76:77], v[76:77], v[154:155] op_sel_hi:[1,0] neg_lo:[0,1] neg_hi:[0,1]
	v_pk_add_f32 v[78:79], v[78:79], v[154:155] op_sel_hi:[1,0] neg_lo:[0,1] neg_hi:[0,1]
	v_pk_add_f32 v[80:81], v[80:81], v[154:155] op_sel_hi:[1,0] neg_lo:[0,1] neg_hi:[0,1]
	v_pk_add_f32 v[82:83], v[82:83], v[154:155] op_sel_hi:[1,0] neg_lo:[0,1] neg_hi:[0,1]
	v_pk_add_f32 v[84:85], v[84:85], v[154:155] op_sel_hi:[1,0] neg_lo:[0,1] neg_hi:[0,1]
	v_pk_add_f32 v[86:87], v[86:87], v[154:155] op_sel_hi:[1,0] neg_lo:[0,1] neg_hi:[0,1]
	v_pk_add_f32 v[88:89], v[88:89], v[154:155] op_sel_hi:[1,0] neg_lo:[0,1] neg_hi:[0,1]
	v_pk_mul_f32 v[90:91], v[58:59], v[58:59]
	v_pk_mul_f32 v[92:93], v[60:61], v[60:61]
	v_pk_mul_f32 v[94:95], v[62:63], v[62:63]
	v_pk_mul_f32 v[96:97], v[64:65], v[64:65]
	v_pk_fma_f32 v[90:91], v[66:67], v[66:67], v[90:91]
	v_pk_fma_f32 v[92:93], v[68:69], v[68:69], v[92:93]
	v_pk_fma_f32 v[94:95], v[70:71], v[70:71], v[94:95]
	v_pk_fma_f32 v[96:97], v[72:73], v[72:73], v[96:97]
	v_pk_fma_f32 v[90:91], v[74:75], v[74:75], v[90:91]
	v_pk_fma_f32 v[92:93], v[76:77], v[76:77], v[92:93]
	v_pk_fma_f32 v[94:95], v[78:79], v[78:79], v[94:95]
	v_pk_fma_f32 v[96:97], v[80:81], v[80:81], v[96:97]
	v_pk_fma_f32 v[90:91], v[82:83], v[82:83], v[90:91]
	v_pk_fma_f32 v[92:93], v[84:85], v[84:85], v[92:93]
	v_pk_fma_f32 v[94:95], v[86:87], v[86:87], v[94:95]
	v_pk_fma_f32 v[96:97], v[88:89], v[88:89], v[96:97]
	v_pk_add_f32 v[90:91], v[90:91], v[92:93]
	v_pk_add_f32 v[94:95], v[94:95], v[96:97]
	s_nop 0
	v_pk_add_f32 v[90:91], v[90:91], v[94:95]
	s_nop 0
	v_add_f32_e32 v158, v90, v91
	ds_read_b128 v[90:93], v7 offset:0
	ds_read_b128 v[94:97], v7 offset:16
	ds_read_b128 v[98:101], v7 offset:32
	ds_read_b128 v[102:105], v7 offset:48
	ds_read_b128 v[106:109], v7 offset:64
	ds_read_b128 v[110:113], v7 offset:80
	ds_read_b128 v[114:117], v7 offset:96
	ds_read_b128 v[118:121], v7 offset:112
	v_add_f32_dpp v159, v158, v158 quad_perm:[1,0,3,2] row_mask:0xf bank_mask:0xf
	s_nop 1
	v_add_f32_dpp v158, v159, v159 quad_perm:[2,3,0,1] row_mask:0xf bank_mask:0xf
	v_mov_b32_e32 v159, 0x358637bd
	ds_read_b128 v[122:125], v7 offset:512
	ds_read_b128 v[126:129], v7 offset:528
	ds_read_b128 v[130:133], v7 offset:544
	ds_read_b128 v[134:137], v7 offset:560
	ds_read_b128 v[138:141], v7 offset:576
	ds_read_b128 v[142:145], v7 offset:592
	ds_read_b128 v[146:149], v7 offset:608
	v_fmamk_f32 v158, v158, 0x3c000000, v159
	s_nop 0
	v_rsq_f32_e32 v156, v158
	v_mul_f32_e32 v159, 0.5, v158
	s_nop 0
	v_mul_f32_e32 v159, v159, v156
	s_nop 0
	v_fma_f32 v159, -v159, v156, 0.5
	s_nop 0
	v_fma_f32 v156, v156, v159, v156
	s_waitcnt lgkmcnt(14)
; #define LAS __attribute__((address_space(3)))
; __device__ __forceinline__ unsigned pk2(float lo, float hi) { return pg8::cvt_pk_bf16_c(lo, hi); }
; __device__ __forceinline__ void sgu_item(LAS unsigned char* lds, const bf16* VA, bf16* AO, const bf16* ZA, const bf16* WSM, const float* ln_g, const float* ln_b, const float* b_sp, ...
;     ...
;         const f32x4* gp = (const f32x4*)(ln_g + g * 128 + q * 32); const f32x4* bp = (const f32x4*)(ln_b + g * 128 + q * 32);
;         LAS unsigned* dst = (LAS unsigned*)(lds + row * VN_PITCH + q * 64);
; #pragma unroll
;         for (int i = 0; i < 8; ++i) { const f32x4 gg = gp[i], bb = bp[i];
;             dst[2 * i] = pk2(v[4 * i] * rstd * gg.x + bb.x, v[4 * i + 1] * rstd * gg.y + bb.y);
;             dst[2 * i + 1] = pk2(v[4 * i + 2] * rstd * gg.z + bb.z, v[4 * i + 3] * rstd * gg.w + bb.w); }
;     }
;     __syncthreads();
	ds_read_b128 v[150:153], v7 offset:624
	s_waitcnt lgkmcnt(7)
	v_pk_mul_f32 v[58:59], v[58:59], v[156:157] op_sel_hi:[1,0]
	v_pk_mul_f32 v[60:61], v[60:61], v[156:157] op_sel_hi:[1,0]
	v_pk_fma_f32 v[58:59], v[58:59], v[90:91], v[122:123]
	v_pk_fma_f32 v[60:61], v[60:61], v[92:93], v[124:125]
	v_cvt_pk_bf16_f32 v58, v58, v59
	v_cvt_pk_bf16_f32 v60, v60, v61
	ds_write2_b32 v3, v58, v60 offset0:0 offset1:1
	s_waitcnt lgkmcnt(7)
	v_pk_mul_f32 v[62:63], v[62:63], v[156:157] op_sel_hi:[1,0]
	v_pk_mul_f32 v[64:65], v[64:65], v[156:157] op_sel_hi:[1,0]
	v_pk_fma_f32 v[62:63], v[62:63], v[94:95], v[126:127]
	v_pk_fma_f32 v[64:65], v[64:65], v[96:97], v[128:129]
	v_cvt_pk_bf16_f32 v62, v62, v63
	v_cvt_pk_bf16_f32 v64, v64, v65
	ds_write2_b32 v3, v62, v64 offset0:2 offset1:3
	s_waitcnt lgkmcnt(7)
	v_pk_mul_f32 v[66:67], v[66:67], v[156:157] op_sel_hi:[1,0]
	v_pk_mul_f32 v[68:69], v[68:69], v[156:157] op_sel_hi:[1,0]
	v_pk_fma_f32 v[66:67], v[66:67], v[98:99], v[130:131]
	v_pk_fma_f32 v[68:69], v[68:69], v[100:101], v[132:133]
	v_cvt_pk_bf16_f32 v66, v66, v67
	v_cvt_pk_bf16_f32 v68, v68, v69
	ds_write2_b32 v3, v66, v68 offset0:4 offset1:5
	s_waitcnt lgkmcnt(7)
	v_pk_mul_f32 v[70:71], v[70:71], v[156:157] op_sel_hi:[1,0]
	v_pk_mul_f32 v[72:73], v[72:73], v[156:157] op_sel_hi:[1,0]
	v_pk_fma_f32 v[70:71], v[70:71], v[102:103], v[134:135]
	v_pk_fma_f32 v[72:73], v[72:73], v[104:105], v[136:137]
	v_cvt_pk_bf16_f32 v70, v70, v71
	v_cvt_pk_bf16_f32 v72, v72, v73
	ds_write2_b32 v3, v70, v72 offset0:6 offset1:7
	s_waitcnt lgkmcnt(7)
	v_pk_mul_f32 v[74:75], v[74:75], v[156:157] op_sel_hi:[1,0]
	v_pk_mul_f32 v[76:77], v[76:77], v[156:157] op_sel_hi:[1,0]
	v_pk_fma_f32 v[74:75], v[74:75], v[106:107], v[138:139]
	v_pk_fma_f32 v[76:77], v[76:77], v[108:109], v[140:141]
	v_cvt_pk_bf16_f32 v74, v74, v75
	v_cvt_pk_bf16_f32 v76, v76, v77
	ds_write2_b32 v3, v74, v76 offset0:8 offset1:9
	s_waitcnt lgkmcnt(7)
	v_pk_mul_f32 v[78:79], v[78:79], v[156:157] op_sel_hi:[1,0]
	v_pk_mul_f32 v[80:81], v[80:81], v[156:157] op_sel_hi:[1,0]
	v_pk_fma_f32 v[78:79], v[78:79], v[110:111], v[142:143]
	v_pk_fma_f32 v[80:81], v[80:81], v[112:113], v[144:145]
	v_cvt_pk_bf16_f32 v78, v78, v79
	v_cvt_pk_bf16_f32 v80, v80, v81
	ds_write2_b32 v3, v78, v80 offset0:10 offset1:11
	s_waitcnt lgkmcnt(7)
	v_pk_mul_f32 v[82:83], v[82:83], v[156:157] op_sel_hi:[1,0]
	v_pk_mul_f32 v[84:85], v[84:85], v[156:157] op_sel_hi:[1,0]
	v_pk_fma_f32 v[82:83], v[82:83], v[114:115], v[146:147]
	v_pk_fma_f32 v[84:85], v[84:85], v[116:117], v[148:149]
	v_cvt_pk_bf16_f32 v82, v82, v83
	v_cvt_pk_bf16_f32 v84, v84, v85
	ds_write2_b32 v3, v82, v84 offset0:12 offset1:13
	s_waitcnt lgkmcnt(7)
	v_pk_mul_f32 v[86:87], v[86:87], v[156:157] op_sel_hi:[1,0]
	v_pk_mul_f32 v[88:89], v[88:89], v[156:157] op_sel_hi:[1,0]
	v_pk_fma_f32 v[86:87], v[86:87], v[118:119], v[150:151]
	v_pk_fma_f32 v[88:89], v[88:89], v[120:121], v[152:153]
	v_cvt_pk_bf16_f32 v86, v86, v87
	v_cvt_pk_bf16_f32 v88, v88, v89
	ds_write2_b32 v3, v86, v88 offset0:14 offset1:15
	s_waitcnt lgkmcnt(0)
	s_barrier
; #define LAS __attribute__((address_space(3)))
; __device__ __forceinline__ void sgu_item(LAS unsigned char* lds, const bf16* VA, bf16* AO, const bf16* ZA, const bf16* WSM, const float* ln_g, const float* ln_b, const float* b_sp, ...
;     ...
;     {
;         const int fr = lane & 15, fq = lane >> 4, c = 16 * wave + fr;
;         bf16x8 X[4];
; #pragma unroll
;         for (int kb = 0; kb < 4; ++kb) {
;             const LAS unsigned short* p = (const LAS unsigned short*)(lds + (32 * kb + 8 * fq) * VN_PITCH + c * 2);
; #pragma unroll
;             for (int j = 0; j < 8; ++j) X[kb][j] = (short)p[j * (VN_PITCH / 2)];
;         }
;         const bf16* wg = WSM + (size_t)g * 16384 + fr * 128 + 8 * fq;
;         f32x4 acc[8];
; #pragma unroll
;         for (int m = 0; m < 8; ++m) { acc[m] = (f32x4){0.f, 0.f, 0.f, 0.f};
; #pragma unroll
;             for (int kb = 0; kb < 4; ++kb) { if (m < 4 && kb >= 2) continue;
;                 const bf16x8 Y = *(const bf16x8*)(wg + m * 2048 + kb * 32);
;                 acc[m] = __builtin_amdgcn_mfma_f32_16x16x32_bf16(X[kb], Y, acc[m], 0, 0, 0); } }
; #pragma unroll
;         for (int m = 0; m < 8; ++m) { const int t = 16 * m + fr; const float bs = b_sp[g * 128 + t];
;             *(LAS f32x4*)(lds + YT_OFF + t * YT_PITCH + (16 * wave + 4 * fq) * 4) = acc[m] + bs; }
;     }
;     __syncthreads();
;     {
;         const int row = tid >> 2, q = tid & 3;
;         v4u* up = (v4u*)(AO + (size_t)(r0 + row) * 2048 + g * 128 + q * 32);
;         const LAS f32x4* yp = (const LAS f32x4*)(lds + YT_OFF + row * YT_PITCH + q * 128);
	ds_read_u16 v90, v4 offset:0
	ds_read_u16 v91, v4 offset:260
	ds_read_u16 v92, v4 offset:520
	ds_read_u16 v93, v4 offset:780
	ds_read_u16 v94, v4 offset:1040
	ds_read_u16 v95, v4 offset:1300
	ds_read_u16 v96, v4 offset:1560
	ds_read_u16 v97, v4 offset:1820
	ds_read_u16 v98, v4 offset:8320
	ds_read_u16 v99, v4 offset:8580
	ds_read_u16 v100, v4 offset:8840
	ds_read_u16 v101, v4 offset:9100
	s_waitcnt lgkmcnt(8)
	v_perm_b32 v122, v91, v90, s21
	v_perm_b32 v123, v93, v92, s21
	ds_read_u16 v102, v4 offset:9360
	ds_read_u16 v103, v4 offset:9620
	ds_read_u16 v104, v4 offset:9880
	ds_read_u16 v105, v4 offset:10140
	s_waitcnt lgkmcnt(8)
	v_perm_b32 v124, v95, v94, s21
	v_perm_b32 v125, v97, v96, s21
	ds_read_u16 v106, v4 offset:16640
	ds_read_u16 v107, v4 offset:16900
	ds_read_u16 v108, v4 offset:17160
	ds_read_u16 v109, v4 offset:17420
	v_mfma_f32_16x16x32_bf16 v[58:61], v[122:125], v[160:163], 0
	v_mfma_f32_16x16x32_bf16 v[62:65], v[122:125], v[168:171], 0
	v_mfma_f32_16x16x32_bf16 v[66:69], v[122:125], v[176:179], 0
	v_mfma_f32_16x16x32_bf16 v[70:73], v[122:125], v[184:187], 0
	s_waitcnt lgkmcnt(8)
	v_perm_b32 v126, v99, v98, s21
	v_perm_b32 v127, v101, v100, s21
	ds_read_u16 v110, v4 offset:17680
	ds_read_u16 v111, v4 offset:17940
	ds_read_u16 v112, v4 offset:18200
	ds_read_u16 v113, v4 offset:18460
	v_mfma_f32_16x16x32_bf16 v[74:77], v[122:125], v[192:195], 0
	v_mfma_f32_16x16x32_bf16 v[78:81], v[122:125], v[208:211], 0
	v_mfma_f32_16x16x32_bf16 v[82:85], v[122:125], v[224:227], 0
	v_mfma_f32_16x16x32_bf16 v[86:89], v[122:125], v[240:243], 0
	s_waitcnt lgkmcnt(8)
	v_perm_b32 v128, v103, v102, s21
	v_perm_b32 v129, v105, v104, s21
	ds_read_u16 v114, v4 offset:24960
	ds_read_u16 v115, v4 offset:25220
	ds_read_u16 v116, v4 offset:25480
	ds_read_u16 v117, v4 offset:25740
	v_mfma_f32_16x16x32_bf16 v[58:61], v[126:129], v[164:167], v[58:61]
	v_mfma_f32_16x16x32_bf16 v[62:65], v[126:129], v[172:175], v[62:65]
	v_mfma_f32_16x16x32_bf16 v[66:69], v[126:129], v[180:183], v[66:69]
	v_mfma_f32_16x16x32_bf16 v[70:73], v[126:129], v[188:191], v[70:73]
	s_waitcnt lgkmcnt(8)
	v_perm_b32 v130, v107, v106, s21
	v_perm_b32 v131, v109, v108, s21
	ds_read_u16 v118, v4 offset:26000
	ds_read_u16 v119, v4 offset:26260
	ds_read_u16 v120, v4 offset:26520
	ds_read_u16 v121, v4 offset:26780
	v_mfma_f32_16x16x32_bf16 v[74:77], v[126:129], v[196:199], v[74:77]
	v_mfma_f32_16x16x32_bf16 v[78:81], v[126:129], v[212:215], v[78:81]
	v_mfma_f32_16x16x32_bf16 v[82:85], v[126:129], v[228:231], v[82:85]
	v_mfma_f32_16x16x32_bf16 v[86:89], v[126:129], v[244:247], v[86:89]
	s_waitcnt lgkmcnt(8)
	v_perm_b32 v132, v111, v110, s21
	v_perm_b32 v133, v113, v112, s21
	s_nop 1
	v_mfma_f32_16x16x32_bf16 v[74:77], v[130:133], v[200:203], v[74:77]
	v_mfma_f32_16x16x32_bf16 v[78:81], v[130:133], v[216:219], v[78:81]
	v_mfma_f32_16x16x32_bf16 v[82:85], v[130:133], v[232:235], v[82:85]
	v_mfma_f32_16x16x32_bf16 v[86:89], v[130:133], v[248:251], v[86:89]
	s_waitcnt lgkmcnt(4)
	v_perm_b32 v134, v115, v114, s21
	v_perm_b32 v135, v117, v116, s21
	s_waitcnt lgkmcnt(0)
	v_perm_b32 v136, v119, v118, s21
	v_perm_b32 v137, v121, v120, s21
	ds_read_b32 v138, v8 offset:0
	ds_read_b32 v139, v8 offset:64
	ds_read_b32 v140, v8 offset:128
	ds_read_b32 v141, v8 offset:192
	ds_read_b32 v142, v8 offset:256
	ds_read_b32 v143, v8 offset:320
	ds_read_b32 v144, v8 offset:384
	ds_read_b32 v145, v8 offset:448
	v_mfma_f32_16x16x32_bf16 v[74:77], v[134:137], v[204:207], v[74:77]
	v_mfma_f32_16x16x32_bf16 v[78:81], v[134:137], v[220:223], v[78:81]
	v_mfma_f32_16x16x32_bf16 v[82:85], v[134:137], v[236:239], v[82:85]
	v_mfma_f32_16x16x32_bf16 v[86:89], v[134:137], v[252:255], v[86:89]
	s_waitcnt lgkmcnt(0)
	v_add_f32_e32 v58, v58, v138
	v_add_f32_e32 v59, v59, v138
	v_add_f32_e32 v60, v60, v138
	v_add_f32_e32 v61, v61, v138
	ds_write_b128 v5, v[58:61] offset:0
	v_add_f32_e32 v62, v62, v139
	v_add_f32_e32 v63, v63, v139
	v_add_f32_e32 v64, v64, v139
	v_add_f32_e32 v65, v65, v139
	ds_write_b128 v5, v[62:65] offset:8448
	v_add_f32_e32 v66, v66, v140
	v_add_f32_e32 v67, v67, v140
	v_add_f32_e32 v68, v68, v140
	v_add_f32_e32 v69, v69, v140
	ds_write_b128 v5, v[66:69] offset:16896
	v_add_f32_e32 v70, v70, v141
	v_add_f32_e32 v71, v71, v141
	v_add_f32_e32 v72, v72, v141
	v_add_f32_e32 v73, v73, v141
	ds_write_b128 v5, v[70:73] offset:25344
	v_add_f32_e32 v74, v74, v142
	v_add_f32_e32 v75, v75, v142
	v_add_f32_e32 v76, v76, v142
	v_add_f32_e32 v77, v77, v142
	ds_write_b128 v5, v[74:77] offset:33792
	v_add_f32_e32 v78, v78, v143
	v_add_f32_e32 v79, v79, v143
	v_add_f32_e32 v80, v80, v143
	v_add_f32_e32 v81, v81, v143
	ds_write_b128 v5, v[78:81] offset:42240
	v_add_f32_e32 v82, v82, v144
	v_add_f32_e32 v83, v83, v144
	v_add_f32_e32 v84, v84, v144
	v_add_f32_e32 v85, v85, v144
	ds_write_b128 v5, v[82:85] offset:50688
	v_add_f32_e32 v86, v86, v145
	v_add_f32_e32 v87, v87, v145
	v_add_f32_e32 v88, v88, v145
	v_add_f32_e32 v89, v89, v145
	ds_write_b128 v5, v[86:89] offset:59136
	s_waitcnt lgkmcnt(0)
	s_barrier
	ds_read_b128 v[58:61], v6 offset:0
	ds_read_b128 v[62:65], v6 offset:16
	ds_read_b128 v[66:69], v6 offset:32
	ds_read_b128 v[70:73], v6 offset:48
	ds_read_b128 v[74:77], v6 offset:64
	ds_read_b128 v[78:81], v6 offset:80
	ds_read_b128 v[82:85], v6 offset:96
	ds_read_b128 v[86:89], v6 offset:112
	s_cmp_lg_u32 s20, 0
	s_cbranch_scc0 .Lsgu_lastw
	s_waitcnt vmcnt(4)
	s_branch .Lsgu_w4

; #define LAS __attribute__((address_space(3)))
; __device__ __forceinline__ unsigned pk2(float lo, float hi) { return pg8::cvt_pk_bf16_c(lo, hi); }
; __device__ __forceinline__ void sgu_item(LAS unsigned char* lds, const bf16* VA, bf16* AO, const bf16* ZA, const bf16* WSM, const float* ln_g, const float* ln_b, const float* b_sp, ...
;     ...
;     {
;         const int row = tid >> 2, q = tid & 3;
;         v4u* up = (v4u*)(AO + (size_t)(r0 + row) * 2048 + g * 128 + q * 32);
;         const LAS f32x4* yp = (const LAS f32x4*)(lds + YT_OFF + row * YT_PITCH + q * 128);
; #pragma unroll
;         for (int i = 0; i < 4; ++i) { const v4u u = ureg[i], z = zreg[i]; const f32x4 y0 = yp[2 * i], y1 = yp[2 * i + 1];
;             v4u o;
;             o.x = pk2(__uint_as_float(u.x << 16) * y0.x * __uint_as_float(z.x << 16), __uint_as_float(u.x & 0xffff0000u) * y0.y * __uint_as_float(z.x & 0xffff0000u));
;             o.y = pk2(__uint_as_float(u.y << 16) * y0.z * __uint_as_float(z.y << 16), __uint_as_float(u.y & 0xffff0000u) * y0.w * __uint_as_float(z.y & 0xffff0000u));
;             o.z = pk2(__uint_as_float(u.z << 16) * y1.x * __uint_as_float(z.z << 16), __uint_as_float(u.z & 0xffff0000u) * y1.y * __uint_as_float(z.z & 0xffff0000u));
;             o.w = pk2(__uint_as_float(u.w << 16) * y1.z * __uint_as_float(z.w << 16), __uint_as_float(u.w & 0xffff0000u) * y1.w * __uint_as_float(z.w & 0xffff0000u));
;             up[i] = o; }
; __global__ void __launch_bounds__(NWAVES * 64, 2) fwd_mega(Args args) {
;     ...
;         if (vcu & 1) { fa::fox_phase((char*)lds_raw, FT, vcu, G); __syncthreads(); { PH_IDS(); v4u vin[4];
;                 if (vcu < 2048) { const v4u* vp = (const v4u*)(VA + (size_t)((vcu >> 3) * 128 + (tid >> 2)) * 1024 + (vcu & 7) * 128 + (tid & 3) * 32);
; #pragma unroll
;                     for (int i = 0; i < 4; ++i) vin[i] = vp[i]; }
;                 for (int it = vcu; it < 2048; it += G) { const int itn = it + G; sgu_item(lds, VA, AO, ZA, WSM, args.in[3], args.in[4], args.in[6], it >> 3, it & 7, tid, lane, wave, vin, itn >> 3, itn & 7, itn < 2048); } } }
;         else { { PH_IDS(); v4u vin[4];
;                 if (vcu < 2048) { const v4u* vp = (const v4u*)(VA + (size_t)((vcu >> 3) * 128 + (tid >> 2)) * 1024 + (vcu & 7) * 128 + (tid & 3) * 32);
; #pragma unroll
;                     for (int i = 0; i < 4; ++i) vin[i] = vp[i]; }
.Lsgu_w4:
	s_waitcnt lgkmcnt(7)
	v_lshlrev_b32_e32 v122, 16, v26
	v_and_b32_e32 v123, 0xffff0000, v26
	v_lshlrev_b32_e32 v124, 16, v42
	v_and_b32_e32 v125, 0xffff0000, v42
	v_pk_mul_f32 v[122:123], v[58:59], v[122:123]
	v_pk_mul_f32 v[122:123], v[122:123], v[124:125]
	v_cvt_pk_bf16_f32 v138, v122, v123
	v_lshlrev_b32_e32 v126, 16, v27
	v_and_b32_e32 v127, 0xffff0000, v27
	v_lshlrev_b32_e32 v128, 16, v43
	v_and_b32_e32 v129, 0xffff0000, v43
	v_pk_mul_f32 v[126:127], v[60:61], v[126:127]
	v_pk_mul_f32 v[126:127], v[126:127], v[128:129]
	v_cvt_pk_bf16_f32 v139, v126, v127
	s_waitcnt lgkmcnt(6)
	v_lshlrev_b32_e32 v130, 16, v28
	v_and_b32_e32 v131, 0xffff0000, v28
	v_lshlrev_b32_e32 v132, 16, v44
	v_and_b32_e32 v133, 0xffff0000, v44
	v_pk_mul_f32 v[130:131], v[62:63], v[130:131]
	v_pk_mul_f32 v[130:131], v[130:131], v[132:133]
	v_cvt_pk_bf16_f32 v140, v130, v131
	v_lshlrev_b32_e32 v134, 16, v29
	v_and_b32_e32 v135, 0xffff0000, v29
	v_lshlrev_b32_e32 v136, 16, v45
	v_and_b32_e32 v137, 0xffff0000, v45
	v_pk_mul_f32 v[134:135], v[64:65], v[134:135]
	v_pk_mul_f32 v[134:135], v[134:135], v[136:137]
	v_cvt_pk_bf16_f32 v141, v134, v135
	global_store_dwordx4 v2, v[138:141], s[12:13] offset:0
	s_waitcnt lgkmcnt(5)
	v_lshlrev_b32_e32 v122, 16, v30
	v_and_b32_e32 v123, 0xffff0000, v30
	v_lshlrev_b32_e32 v124, 16, v46
	v_and_b32_e32 v125, 0xffff0000, v46
	v_pk_mul_f32 v[122:123], v[66:67], v[122:123]
	v_pk_mul_f32 v[122:123], v[122:123], v[124:125]
	v_cvt_pk_bf16_f32 v142, v122, v123
	v_lshlrev_b32_e32 v126, 16, v31
	v_and_b32_e32 v127, 0xffff0000, v31
	v_lshlrev_b32_e32 v128, 16, v47
	v_and_b32_e32 v129, 0xffff0000, v47
	v_pk_mul_f32 v[126:127], v[68:69], v[126:127]
	v_pk_mul_f32 v[126:127], v[126:127], v[128:129]
	v_cvt_pk_bf16_f32 v143, v126, v127
	s_waitcnt lgkmcnt(4)
	v_lshlrev_b32_e32 v130, 16, v32
	v_and_b32_e32 v131, 0xffff0000, v32
	v_lshlrev_b32_e32 v132, 16, v48
	v_and_b32_e32 v133, 0xffff0000, v48
	v_pk_mul_f32 v[130:131], v[70:71], v[130:131]
	v_pk_mul_f32 v[130:131], v[130:131], v[132:133]
	v_cvt_pk_bf16_f32 v144, v130, v131
	v_lshlrev_b32_e32 v134, 16, v33
	v_and_b32_e32 v135, 0xffff0000, v33
	v_lshlrev_b32_e32 v136, 16, v49
	v_and_b32_e32 v137, 0xffff0000, v49
	v_pk_mul_f32 v[134:135], v[72:73], v[134:135]
	v_pk_mul_f32 v[134:135], v[134:135], v[136:137]
	v_cvt_pk_bf16_f32 v145, v134, v135
	global_store_dwordx4 v2, v[142:145], s[12:13] offset:16
	s_waitcnt lgkmcnt(3)
	v_lshlrev_b32_e32 v122, 16, v34
	v_and_b32_e32 v123, 0xffff0000, v34
	v_lshlrev_b32_e32 v124, 16, v50
	v_and_b32_e32 v125, 0xffff0000, v50
	v_pk_mul_f32 v[122:123], v[74:75], v[122:123]
	v_pk_mul_f32 v[122:123], v[122:123], v[124:125]
	v_cvt_pk_bf16_f32 v146, v122, v123
	v_lshlrev_b32_e32 v126, 16, v35
	v_and_b32_e32 v127, 0xffff0000, v35
	v_lshlrev_b32_e32 v128, 16, v51
	v_and_b32_e32 v129, 0xffff0000, v51
	v_pk_mul_f32 v[126:127], v[76:77], v[126:127]
	v_pk_mul_f32 v[126:127], v[126:127], v[128:129]
	v_cvt_pk_bf16_f32 v147, v126, v127
	s_waitcnt lgkmcnt(2)
	v_lshlrev_b32_e32 v130, 16, v36
	v_and_b32_e32 v131, 0xffff0000, v36
	v_lshlrev_b32_e32 v132, 16, v52
	v_and_b32_e32 v133, 0xffff0000, v52
	v_pk_mul_f32 v[130:131], v[78:79], v[130:131]
	v_pk_mul_f32 v[130:131], v[130:131], v[132:133]
	v_cvt_pk_bf16_f32 v148, v130, v131
	v_lshlrev_b32_e32 v134, 16, v37
	v_and_b32_e32 v135, 0xffff0000, v37
	v_lshlrev_b32_e32 v136, 16, v53
	v_and_b32_e32 v137, 0xffff0000, v53
	v_pk_mul_f32 v[134:135], v[80:81], v[134:135]
	v_pk_mul_f32 v[134:135], v[134:135], v[136:137]
	v_cvt_pk_bf16_f32 v149, v134, v135
	global_store_dwordx4 v2, v[146:149], s[12:13] offset:32
	s_waitcnt lgkmcnt(1)
	v_lshlrev_b32_e32 v122, 16, v38
	v_and_b32_e32 v123, 0xffff0000, v38
	v_lshlrev_b32_e32 v124, 16, v54
	v_and_b32_e32 v125, 0xffff0000, v54
	v_pk_mul_f32 v[122:123], v[82:83], v[122:123]
	v_pk_mul_f32 v[122:123], v[122:123], v[124:125]
	v_cvt_pk_bf16_f32 v150, v122, v123
	v_lshlrev_b32_e32 v126, 16, v39
	v_and_b32_e32 v127, 0xffff0000, v39
	v_lshlrev_b32_e32 v128, 16, v55
	v_and_b32_e32 v129, 0xffff0000, v55
	v_pk_mul_f32 v[126:127], v[84:85], v[126:127]
	v_pk_mul_f32 v[126:127], v[126:127], v[128:129]
	v_cvt_pk_bf16_f32 v151, v126, v127
	s_waitcnt lgkmcnt(0)
	v_lshlrev_b32_e32 v130, 16, v40
	v_and_b32_e32 v131, 0xffff0000, v40
	v_lshlrev_b32_e32 v132, 16, v56
	v_and_b32_e32 v133, 0xffff0000, v56
	v_pk_mul_f32 v[130:131], v[86:87], v[130:131]
	v_pk_mul_f32 v[130:131], v[130:131], v[132:133]
	v_cvt_pk_bf16_f32 v152, v130, v131
	v_lshlrev_b32_e32 v134, 16, v41
	v_and_b32_e32 v135, 0xffff0000, v41
	v_lshlrev_b32_e32 v136, 16, v57
	v_and_b32_e32 v137, 0xffff0000, v57
	v_pk_mul_f32 v[134:135], v[88:89], v[134:135]
	v_pk_mul_f32 v[134:135], v[134:135], v[136:137]
	v_cvt_pk_bf16_f32 v153, v134, v135
	global_store_dwordx4 v2, v[150:153], s[12:13] offset:48
	s_cmp_lg_u32 s20, 0
	s_cbranch_scc0 .Lsgu_done
	global_load_dwordx4 v[26:29], v2, s[16:17] offset:0
	global_load_dwordx4 v[30:33], v2, s[16:17] offset:16
	global_load_dwordx4 v[34:37], v2, s[16:17] offset:32
	global_load_dwordx4 v[38:41], v2, s[16:17] offset:48
	global_load_dwordx4 v[42:45], v1, s[18:19] offset:0
	global_load_dwordx4 v[46:49], v1, s[18:19] offset:16
	global_load_dwordx4 v[50:53], v1, s[18:19] offset:32
	global_load_dwordx4 v[54:57], v1, s[18:19] offset:48
	s_mov_b32 s4, s5
	s_branch .Lsgu_item
.Lsgu_done:
	s_bitcmp1_b32 s86, 0
	s_cbranch_scc1 .LBB0_324
